# EpiResid epilogue: residual-input loads marked nt (streamed once)
# baseline (speedup 1.0000x reference)
; __device__ __forceinline__ unsigned cvt_pk_bf16(float lo, float hi) { const f32x2 v = {lo, hi}; return __builtin_bit_cast(unsigned, __builtin_convertvector(v, bf16x2_t)); }
; __device__ __forceinline__ float dot4(f32x4 v) { return (v.x * v.x + v.y * v.y) + (v.z * v.z + v.w * v.w); }
;     template <int A0, int A1> __device__ __forceinline__ void run(const f32x4 (&acc)[2][2][4][2], const Unit& u, int wr, int wc, int fr, int fq) const {
;     ...
;         for (int bj = 0; bj < 2; ++bj) {
;             const int col = u.pn * 256 + bj * 128 + wc * 32 + fq * 8;
;             const f32x4 gv0 = *(const f32x4*)(gate + s * NMOD + col) * gmul, gv1 = *(const f32x4*)(gate + s * NMOD + col + 4) * gmul;
;             f32x4 wv0 = (f32x4){0.f, 0.f, 0.f, 0.f}, wv1 = wv0;
;             if (has_next) { wv0 = *(const f32x4*)(nw + col) * (*(const f32x4*)(nscale + s * NMOD + col) + 1.0f); wv1 = *(const f32x4*)(nw + col + 4) * (*(const f32x4*)(nscale + s * NMOD + col + 4) + 1.0f); }
; #pragma unroll
;             for (int ai = A0; ai < A1; ++ai)
; #pragma unroll
;                 for (int m = 0; m < 4; ++m) {
;                     const size_t off = (size_t)(row0 + ai * 128 + m * 16) * DM + col;
;                     const f32x4 x0 = *(const f32x4*)(xo + off) + gv0 * acc[ai][bj][m][0];
;                     const f32x4 x1 = *(const f32x4*)(xo + off + 4) + gv1 * acc[ai][bj][m][1];
;                     *(f32x4*)(xn + off) = x0; *(f32x4*)(xn + off + 4) = x1;
;                     ssq[ai][m] += dot4(x0) + dot4(x1);
;                     if (has_next) { const f32x4 y0 = x0 * wv0, y1 = x1 * wv1; u32x4 w; w.x = cvt_pk_bf16(y0.x, y0.y); w.y = cvt_pk_bf16(y0.z, y0.w); w.z = cvt_pk_bf16(y1.x, y1.y); w.w = cvt_pk_bf16(y1.z, y1.w); *(u32x4*)(Xw + off) = w; }
;                 }
.LBB0_1239:
	v_lshl_add_u32 v152, s67, 8, v240
	v_ashrrev_i32_e32 v153, 31, v152
	v_lshlrev_b64 v[168:169], 10, v[152:153]
	s_cmp_lt_i32 s67, 64
	v_lshl_add_u64 v[154:155], v[168:169], 0, v[184:185]
	s_cselect_b32 s37, s29, s84
	s_cselect_b32 s36, s28, s43
	v_lshlrev_b64 v[164:165], 2, v[154:155]
	v_lshl_add_u64 v[216:217], s[36:37], 0, v[164:165]
	global_load_dwordx4 v[156:159], v[216:217], off nt
	global_load_dwordx4 v[160:163], v[216:217], off offset:16 nt
	v_mov_b32_e32 v145, v144
	s_waitcnt vmcnt(0)
	v_pk_mul_f32 v[134:135], v[146:147], v[134:135]
	v_pk_mul_f32 v[130:131], v[146:147], v[130:131]
	s_cselect_b32 s39, s83, s71
	s_cselect_b32 s38, s82, s85
	v_pk_mul_f32 v[136:137], v[144:145], v[136:137]
	v_pk_mul_f32 v[132:133], v[144:145], v[132:133]
	s_and_b64 vcc, exec, s[8:9]
	v_lshl_add_u64 v[222:223], s[38:39], 0, v[164:165]
	v_pk_fma_f32 v[94:95], v[94:95], v[136:137], v[158:159]
	v_pk_fma_f32 v[92:93], v[92:93], v[134:135], v[156:157]
	v_pk_fma_f32 v[90:91], v[90:91], v[132:133], v[162:163]
	v_pk_fma_f32 v[88:89], v[88:89], v[130:131], v[160:161]
	global_store_dwordx4 v[222:223], v[92:95], off
	global_store_dwordx4 v[222:223], v[88:91], off offset:16
	s_cbranch_vccnz .LBB0_1241
	v_pk_mul_f32 v[158:159], v[230:231], v[94:95]
	v_pk_mul_f32 v[156:157], v[228:229], v[92:93]
	v_pk_mul_f32 v[160:161], v[226:227], v[90:91]
	v_pk_mul_f32 v[162:163], v[224:225], v[88:89]
	v_cvt_pk_bf16_f32 v156, v156, v157
	v_cvt_pk_bf16_f32 v157, v158, v159
	v_cvt_pk_bf16_f32 v158, v162, v163
	v_cvt_pk_bf16_f32 v159, v160, v161
	v_lshl_add_u64 v[154:155], v[154:155], 1, s[22:23]
	global_store_dwordx4 v[154:155], v[156:159], off
.LBB0_1241:
	v_or_b32_e32 v154, 16, v152
	v_ashrrev_i32_e32 v155, 31, v154
	v_lshlrev_b64 v[170:171], 10, v[154:155]
	v_lshl_add_u64 v[156:157], v[170:171], 0, v[184:185]
	v_lshlrev_b64 v[166:167], 2, v[156:157]
	v_lshl_add_u64 v[182:183], s[36:37], 0, v[166:167]
	global_load_dwordx4 v[158:161], v[182:183], off nt
	global_load_dwordx4 v[162:165], v[182:183], off offset:16 nt
	s_and_b64 vcc, exec, s[8:9]
	v_lshl_add_u64 v[180:181], s[38:39], 0, v[166:167]
	s_waitcnt vmcnt(1)
	v_pk_fma_f32 v[110:111], v[110:111], v[136:137], v[160:161]
	v_pk_fma_f32 v[108:109], v[108:109], v[134:135], v[158:159]
	s_waitcnt vmcnt(0)
	v_pk_fma_f32 v[102:103], v[102:103], v[132:133], v[164:165]
	v_pk_fma_f32 v[100:101], v[100:101], v[130:131], v[162:163]
	global_store_dwordx4 v[180:181], v[108:111], off
	global_store_dwordx4 v[180:181], v[100:103], off offset:16
	s_cbranch_vccnz .LBB0_1243
	v_pk_mul_f32 v[160:161], v[230:231], v[110:111]
	v_pk_mul_f32 v[158:159], v[228:229], v[108:109]
	v_pk_mul_f32 v[162:163], v[226:227], v[102:103]
	v_pk_mul_f32 v[164:165], v[224:225], v[100:101]
	v_cvt_pk_bf16_f32 v158, v158, v159
	v_cvt_pk_bf16_f32 v159, v160, v161
	v_cvt_pk_bf16_f32 v160, v164, v165
	v_cvt_pk_bf16_f32 v161, v162, v163
	v_lshl_add_u64 v[156:157], v[156:157], 1, s[22:23]
	global_store_dwordx4 v[156:157], v[158:161], off
.LBB0_1243:
	v_or_b32_e32 v156, 32, v152
	v_ashrrev_i32_e32 v157, 31, v156
	v_lshlrev_b64 v[172:173], 10, v[156:157]
	v_lshl_add_u64 v[158:159], v[172:173], 0, v[184:185]
	v_lshlrev_b64 v[174:175], 2, v[158:159]
	v_lshl_add_u64 v[188:189], s[36:37], 0, v[174:175]
	global_load_dwordx4 v[160:163], v[188:189], off nt
	global_load_dwordx4 v[164:167], v[188:189], off offset:16 nt
	s_and_b64 vcc, exec, s[8:9]
	v_lshl_add_u64 v[186:187], s[38:39], 0, v[174:175]
	s_waitcnt vmcnt(1)
	v_pk_fma_f32 v[118:119], v[118:119], v[136:137], v[162:163]
	v_pk_fma_f32 v[116:117], v[116:117], v[134:135], v[160:161]
	s_waitcnt vmcnt(0)
	v_pk_fma_f32 v[114:115], v[114:115], v[132:133], v[166:167]
	v_pk_fma_f32 v[112:113], v[112:113], v[130:131], v[164:165]
	global_store_dwordx4 v[186:187], v[116:119], off
	global_store_dwordx4 v[186:187], v[112:115], off offset:16
	s_cbranch_vccnz .LBB0_1245
	v_pk_mul_f32 v[162:163], v[230:231], v[118:119]
	v_pk_mul_f32 v[160:161], v[228:229], v[116:117]
	v_pk_mul_f32 v[164:165], v[226:227], v[114:115]
	v_pk_mul_f32 v[166:167], v[224:225], v[112:113]
	v_cvt_pk_bf16_f32 v160, v160, v161
	v_cvt_pk_bf16_f32 v161, v162, v163
	v_cvt_pk_bf16_f32 v162, v166, v167
	v_cvt_pk_bf16_f32 v163, v164, v165
	v_lshl_add_u64 v[158:159], v[158:159], 1, s[22:23]
	global_store_dwordx4 v[158:159], v[160:163], off
.LBB0_1245:
	v_or_b32_e32 v158, 48, v152
	v_ashrrev_i32_e32 v159, 31, v158
	v_lshlrev_b64 v[174:175], 10, v[158:159]
	v_lshl_add_u64 v[160:161], v[174:175], 0, v[184:185]
	v_lshlrev_b64 v[166:167], 2, v[160:161]
	v_lshl_add_u64 v[196:197], s[36:37], 0, v[166:167]
	global_load_dwordx4 v[162:165], v[196:197], off nt
	global_load_dwordx4 v[176:179], v[196:197], off offset:16 nt
	s_and_b64 vcc, exec, s[8:9]
	v_lshl_add_u64 v[194:195], s[38:39], 0, v[166:167]
	s_waitcnt vmcnt(1)
	v_pk_fma_f32 v[126:127], v[126:127], v[136:137], v[164:165]
	v_pk_fma_f32 v[124:125], v[124:125], v[134:135], v[162:163]
	s_waitcnt vmcnt(0)
	v_pk_fma_f32 v[122:123], v[122:123], v[132:133], v[178:179]
	v_pk_fma_f32 v[120:121], v[120:121], v[130:131], v[176:177]
	global_store_dwordx4 v[194:195], v[124:127], off
	global_store_dwordx4 v[194:195], v[120:123], off offset:16
	s_cbranch_vccnz .LBB0_1247
	v_pk_mul_f32 v[164:165], v[230:231], v[126:127]
	v_pk_mul_f32 v[162:163], v[228:229], v[124:125]
	v_pk_mul_f32 v[166:167], v[226:227], v[122:123]
	v_pk_mul_f32 v[176:177], v[224:225], v[120:121]
	v_cvt_pk_bf16_f32 v162, v162, v163
	v_cvt_pk_bf16_f32 v163, v164, v165
	v_cvt_pk_bf16_f32 v164, v176, v177
	v_cvt_pk_bf16_f32 v165, v166, v167
	v_lshl_add_u64 v[160:161], v[160:161], 1, s[22:23]
	global_store_dwordx4 v[160:161], v[162:165], off
; __device__ __forceinline__ unsigned cvt_pk_bf16(float lo, float hi) { const f32x2 v = {lo, hi}; return __builtin_bit_cast(unsigned, __builtin_convertvector(v, bf16x2_t)); }
; __device__ __forceinline__ float dot4(f32x4 v) { return (v.x * v.x + v.y * v.y) + (v.z * v.z + v.w * v.w); }
;     template <int A0, int A1> __device__ __forceinline__ void run(const f32x4 (&acc)[2][2][4][2], const Unit& u, int wr, int wc, int fr, int fq) const {
;     ...
;             for (int ai = A0; ai < A1; ++ai)
; #pragma unroll
;                 for (int m = 0; m < 4; ++m) {
;                     const size_t off = (size_t)(row0 + ai * 128 + m * 16) * DM + col;
;                     const f32x4 x0 = *(const f32x4*)(xo + off) + gv0 * acc[ai][bj][m][0];
;                     const f32x4 x1 = *(const f32x4*)(xo + off + 4) + gv1 * acc[ai][bj][m][1];
;                     *(f32x4*)(xn + off) = x0; *(f32x4*)(xn + off + 4) = x1;
;                     ssq[ai][m] += dot4(x0) + dot4(x1);
;                     if (has_next) { const f32x4 y0 = x0 * wv0, y1 = x1 * wv1; u32x4 w; w.x = cvt_pk_bf16(y0.x, y0.y); w.y = cvt_pk_bf16(y0.z, y0.w); w.z = cvt_pk_bf16(y1.x, y1.y); w.w = cvt_pk_bf16(y1.z, y1.w); *(u32x4*)(Xw + off) = w; }
;                 }
.LBB0_1247:
	v_add_u32_e32 v160, 0x80, v152
	v_ashrrev_i32_e32 v161, 31, v160
	v_lshlrev_b64 v[176:177], 10, v[160:161]
	v_lshl_add_u64 v[162:163], v[176:177], 0, v[184:185]
	v_lshlrev_b64 v[178:179], 2, v[162:163]
	v_lshl_add_u64 v[200:201], s[36:37], 0, v[178:179]
	global_load_dwordx4 v[164:167], v[200:201], off nt
	global_load_dwordx4 v[190:193], v[200:201], off offset:16 nt
	s_and_b64 vcc, exec, s[8:9]
	v_lshl_add_u64 v[198:199], s[38:39], 0, v[178:179]
	s_waitcnt vmcnt(1)
	v_pk_fma_f32 v[106:107], v[106:107], v[136:137], v[166:167]
	v_pk_fma_f32 v[104:105], v[104:105], v[134:135], v[164:165]
	s_waitcnt vmcnt(0)
	v_pk_fma_f32 v[98:99], v[98:99], v[132:133], v[192:193]
	v_pk_fma_f32 v[96:97], v[96:97], v[130:131], v[190:191]
	global_store_dwordx4 v[198:199], v[104:107], off
	global_store_dwordx4 v[198:199], v[96:99], off offset:16
	s_cbranch_vccnz .LBB0_1249
	v_pk_mul_f32 v[166:167], v[230:231], v[106:107]
	v_pk_mul_f32 v[164:165], v[228:229], v[104:105]
	v_pk_mul_f32 v[178:179], v[226:227], v[98:99]
	v_pk_mul_f32 v[190:191], v[224:225], v[96:97]
	v_cvt_pk_bf16_f32 v164, v164, v165
	v_cvt_pk_bf16_f32 v165, v166, v167
	v_cvt_pk_bf16_f32 v166, v190, v191
	v_cvt_pk_bf16_f32 v167, v178, v179
	v_lshl_add_u64 v[162:163], v[162:163], 1, s[22:23]
	global_store_dwordx4 v[162:163], v[164:167], off
.LBB0_1249:
	v_add_u32_e32 v162, 0x90, v152
	v_ashrrev_i32_e32 v163, 31, v162
	v_lshlrev_b64 v[178:179], 10, v[162:163]
	v_lshl_add_u64 v[164:165], v[178:179], 0, v[184:185]
	v_lshlrev_b64 v[166:167], 2, v[164:165]
	v_lshl_add_u64 v[204:205], s[36:37], 0, v[166:167]
	global_load_dwordx4 v[190:193], v[204:205], off nt
	global_load_dwordx4 v[206:209], v[204:205], off offset:16 nt
	s_and_b64 vcc, exec, s[8:9]
	v_lshl_add_u64 v[202:203], s[38:39], 0, v[166:167]
	s_waitcnt vmcnt(1)
	v_pk_fma_f32 v[86:87], v[86:87], v[136:137], v[192:193]
	v_pk_fma_f32 v[84:85], v[84:85], v[134:135], v[190:191]
	s_waitcnt vmcnt(0)
	v_pk_fma_f32 v[82:83], v[82:83], v[132:133], v[208:209]
	v_pk_fma_f32 v[80:81], v[80:81], v[130:131], v[206:207]
	global_store_dwordx4 v[202:203], v[84:87], off
	global_store_dwordx4 v[202:203], v[80:83], off offset:16
	s_cbranch_vccnz .LBB0_1251
	v_pk_mul_f32 v[166:167], v[230:231], v[86:87]
	v_pk_mul_f32 v[190:191], v[228:229], v[84:85]
	v_pk_mul_f32 v[206:207], v[226:227], v[82:83]
	v_pk_mul_f32 v[192:193], v[224:225], v[80:81]
	v_cvt_pk_bf16_f32 v190, v190, v191
	v_cvt_pk_bf16_f32 v191, v166, v167
	v_cvt_pk_bf16_f32 v192, v192, v193
	v_cvt_pk_bf16_f32 v193, v206, v207
	v_lshl_add_u64 v[164:165], v[164:165], 1, s[22:23]
	global_store_dwordx4 v[164:165], v[190:193], off
.LBB0_1251:
	v_add_u32_e32 v164, 0xa0, v152
	v_ashrrev_i32_e32 v165, 31, v164
	v_lshlrev_b64 v[190:191], 10, v[164:165]
	v_lshl_add_u64 v[166:167], v[190:191], 0, v[184:185]
	v_lshlrev_b64 v[192:193], 2, v[166:167]
	v_lshl_add_u64 v[208:209], s[36:37], 0, v[192:193]
	global_load_dwordx4 v[210:213], v[208:209], off nt
	global_load_dwordx4 v[232:235], v[208:209], off offset:16 nt
	s_and_b64 vcc, exec, s[8:9]
	v_lshl_add_u64 v[206:207], s[38:39], 0, v[192:193]
	s_waitcnt vmcnt(1)
	v_pk_fma_f32 v[78:79], v[78:79], v[136:137], v[212:213]
	v_pk_fma_f32 v[76:77], v[76:77], v[134:135], v[210:211]
	s_waitcnt vmcnt(0)
	v_pk_fma_f32 v[74:75], v[74:75], v[132:133], v[234:235]
	v_pk_fma_f32 v[72:73], v[72:73], v[130:131], v[232:233]
	global_store_dwordx4 v[206:207], v[76:79], off
	global_store_dwordx4 v[206:207], v[72:75], off offset:16
	s_cbranch_vccnz .LBB0_1253
	v_pk_mul_f32 v[192:193], v[230:231], v[78:79]
	v_pk_mul_f32 v[210:211], v[228:229], v[76:77]
	v_pk_mul_f32 v[232:233], v[226:227], v[74:75]
	v_pk_mul_f32 v[212:213], v[224:225], v[72:73]
	v_cvt_pk_bf16_f32 v210, v210, v211
	v_cvt_pk_bf16_f32 v211, v192, v193
	v_cvt_pk_bf16_f32 v212, v212, v213
	v_cvt_pk_bf16_f32 v213, v232, v233
	v_lshl_add_u64 v[166:167], v[166:167], 1, s[22:23]
	global_store_dwordx4 v[166:167], v[210:213], off
.LBB0_1253:
	v_add_u32_e32 v166, 0xb0, v152
	v_ashrrev_i32_e32 v167, 31, v166
	v_lshlrev_b64 v[192:193], 10, v[166:167]
	v_lshl_add_u64 v[232:233], v[192:193], 0, v[184:185]
	v_lshlrev_b64 v[210:211], 2, v[232:233]
	v_lshl_add_u64 v[212:213], s[36:37], 0, v[210:211]
	global_load_dwordx4 v[234:237], v[212:213], off nt
	global_load_dwordx4 v[246:249], v[212:213], off offset:16 nt
	s_and_b64 vcc, exec, s[8:9]
	v_lshl_add_u64 v[210:211], s[38:39], 0, v[210:211]
	s_waitcnt vmcnt(1)
	v_pk_fma_f32 v[70:71], v[70:71], v[136:137], v[236:237]
	v_pk_fma_f32 v[68:69], v[68:69], v[134:135], v[234:235]
	s_waitcnt vmcnt(0)
	v_pk_fma_f32 v[66:67], v[66:67], v[132:133], v[248:249]
	v_pk_fma_f32 v[64:65], v[64:65], v[130:131], v[246:247]
	global_store_dwordx4 v[210:211], v[68:71], off
	global_store_dwordx4 v[210:211], v[64:67], off offset:16
	s_cbranch_vccnz .LBB0_1255
	v_pk_mul_f32 v[132:133], v[230:231], v[70:71]
	v_pk_mul_f32 v[130:131], v[228:229], v[68:69]
	v_pk_mul_f32 v[134:135], v[226:227], v[66:67]
	v_pk_mul_f32 v[136:137], v[224:225], v[64:65]
	v_cvt_pk_bf16_f32 v130, v130, v131
	v_cvt_pk_bf16_f32 v131, v132, v133
	v_cvt_pk_bf16_f32 v132, v136, v137
	v_cvt_pk_bf16_f32 v133, v134, v135
	v_lshl_add_u64 v[134:135], v[232:233], 1, s[22:23]
	global_store_dwordx4 v[134:135], v[130:133], off

; __device__ __forceinline__ unsigned cvt_pk_bf16(float lo, float hi) { const f32x2 v = {lo, hi}; return __builtin_bit_cast(unsigned, __builtin_convertvector(v, bf16x2_t)); }
; __device__ __forceinline__ float dot4(f32x4 v) { return (v.x * v.x + v.y * v.y) + (v.z * v.z + v.w * v.w); }
;     template <int A0, int A1> __device__ __forceinline__ void run(const f32x4 (&acc)[2][2][4][2], const Unit& u, int wr, int wc, int fr, int fq) const {
;     ...
;         for (int bj = 0; bj < 2; ++bj) {
;             const int col = u.pn * 256 + bj * 128 + wc * 32 + fq * 8;
;             const f32x4 gv0 = *(const f32x4*)(gate + s * NMOD + col) * gmul, gv1 = *(const f32x4*)(gate + s * NMOD + col + 4) * gmul;
;             f32x4 wv0 = (f32x4){0.f, 0.f, 0.f, 0.f}, wv1 = wv0;
;             if (has_next) { wv0 = *(const f32x4*)(nw + col) * (*(const f32x4*)(nscale + s * NMOD + col) + 1.0f); wv1 = *(const f32x4*)(nw + col + 4) * (*(const f32x4*)(nscale + s * NMOD + col + 4) + 1.0f); }
; #pragma unroll
;             for (int ai = A0; ai < A1; ++ai)
; #pragma unroll
;                 for (int m = 0; m < 4; ++m) {
;                     const size_t off = (size_t)(row0 + ai * 128 + m * 16) * DM + col;
;                     const f32x4 x0 = *(const f32x4*)(xo + off) + gv0 * acc[ai][bj][m][0];
;                     const f32x4 x1 = *(const f32x4*)(xo + off + 4) + gv1 * acc[ai][bj][m][1];
;                     *(f32x4*)(xn + off) = x0; *(f32x4*)(xn + off + 4) = x1;
;                     ssq[ai][m] += dot4(x0) + dot4(x1);
;                     if (has_next) { const f32x4 y0 = x0 * wv0, y1 = x1 * wv1; u32x4 w; w.x = cvt_pk_bf16(y0.x, y0.y); w.y = cvt_pk_bf16(y0.z, y0.w); w.z = cvt_pk_bf16(y1.x, y1.y); w.w = cvt_pk_bf16(y1.z, y1.w); *(u32x4*)(Xw + off) = w; }
;                 }
.LBB0_1257:
	global_load_dwordx4 v[230:233], v[216:217], off offset:528 nt
	s_nop 0
	global_load_dwordx4 v[214:217], v[216:217], off offset:512 nt
	v_mov_b32_e32 v145, v144
	v_or_b32_e32 v184, 0x80, v184
	s_waitcnt vmcnt(2)
	v_pk_mul_f32 v[136:137], v[144:145], v[136:137]
	v_pk_mul_f32 v[134:135], v[146:147], v[134:135]
	v_pk_mul_f32 v[132:133], v[144:145], v[132:133]
	v_pk_mul_f32 v[130:131], v[146:147], v[130:131]
	v_ashrrev_i32_e32 v185, 31, v184
	s_and_b64 vcc, exec, s[8:9]
	s_waitcnt vmcnt(1)
	v_pk_fma_f32 v[58:59], v[58:59], v[132:133], v[232:233]
	s_waitcnt vmcnt(0)
	v_pk_fma_f32 v[62:63], v[62:63], v[136:137], v[216:217]
	v_pk_fma_f32 v[60:61], v[60:61], v[134:135], v[214:215]
	v_pk_fma_f32 v[56:57], v[56:57], v[130:131], v[230:231]
	global_store_dwordx4 v[222:223], v[60:63], off offset:512
	global_store_dwordx4 v[222:223], v[56:59], off offset:528
	s_cbranch_vccnz .LBB0_1259
	v_lshl_add_u64 v[168:169], v[168:169], 0, v[184:185]
	v_pk_mul_f32 v[216:217], v[228:229], v[62:63]
	v_pk_mul_f32 v[214:215], v[226:227], v[60:61]
	v_pk_mul_f32 v[218:219], v[224:225], v[58:59]
	v_pk_mul_f32 v[222:223], v[220:221], v[56:57]
	v_cvt_pk_bf16_f32 v214, v214, v215
	v_cvt_pk_bf16_f32 v215, v216, v217
	v_cvt_pk_bf16_f32 v216, v222, v223
	v_cvt_pk_bf16_f32 v217, v218, v219
	v_lshl_add_u64 v[168:169], v[168:169], 1, s[22:23]
	global_store_dwordx4 v[168:169], v[214:217], off
.LBB0_1259:
	global_load_dwordx4 v[214:217], v[182:183], off offset:512 nt
	s_nop 0
	global_load_dwordx4 v[230:233], v[182:183], off offset:528 nt
	s_and_b64 vcc, exec, s[8:9]
	s_waitcnt vmcnt(1)
	v_pk_fma_f32 v[54:55], v[54:55], v[136:137], v[216:217]
	v_pk_fma_f32 v[52:53], v[52:53], v[134:135], v[214:215]
	s_waitcnt vmcnt(0)
	v_pk_fma_f32 v[50:51], v[50:51], v[132:133], v[232:233]
	v_pk_fma_f32 v[48:49], v[48:49], v[130:131], v[230:231]
	global_store_dwordx4 v[180:181], v[52:55], off offset:512
	global_store_dwordx4 v[180:181], v[48:51], off offset:528
	s_cbranch_vccnz .LBB0_1261
	v_lshl_add_u64 v[180:181], v[170:171], 0, v[184:185]
	v_pk_mul_f32 v[170:171], v[228:229], v[54:55]
	v_pk_mul_f32 v[168:169], v[226:227], v[52:53]
	v_pk_mul_f32 v[182:183], v[224:225], v[50:51]
	v_pk_mul_f32 v[214:215], v[220:221], v[48:49]
	v_cvt_pk_bf16_f32 v168, v168, v169
	v_cvt_pk_bf16_f32 v169, v170, v171
	v_cvt_pk_bf16_f32 v170, v214, v215
	v_cvt_pk_bf16_f32 v171, v182, v183
	v_lshl_add_u64 v[180:181], v[180:181], 1, s[22:23]
	global_store_dwordx4 v[180:181], v[168:171], off
.LBB0_1261:
	global_load_dwordx4 v[168:171], v[188:189], off offset:512 nt
	s_nop 0
	global_load_dwordx4 v[180:183], v[188:189], off offset:528 nt
	s_and_b64 vcc, exec, s[8:9]
	s_waitcnt vmcnt(1)
	v_pk_fma_f32 v[46:47], v[46:47], v[136:137], v[170:171]
	v_pk_fma_f32 v[44:45], v[44:45], v[134:135], v[168:169]
	s_waitcnt vmcnt(0)
	v_pk_fma_f32 v[42:43], v[42:43], v[132:133], v[182:183]
	v_pk_fma_f32 v[40:41], v[40:41], v[130:131], v[180:181]
	global_store_dwordx4 v[186:187], v[44:47], off offset:512
	global_store_dwordx4 v[186:187], v[40:43], off offset:528
	s_cbranch_vccnz .LBB0_1263
	v_lshl_add_u64 v[172:173], v[172:173], 0, v[184:185]
	v_pk_mul_f32 v[170:171], v[228:229], v[46:47]
	v_pk_mul_f32 v[168:169], v[226:227], v[44:45]
	v_pk_mul_f32 v[180:181], v[224:225], v[42:43]
	v_pk_mul_f32 v[182:183], v[220:221], v[40:41]
	v_cvt_pk_bf16_f32 v168, v168, v169
	v_cvt_pk_bf16_f32 v169, v170, v171
	v_cvt_pk_bf16_f32 v170, v182, v183
	v_cvt_pk_bf16_f32 v171, v180, v181
	v_lshl_add_u64 v[172:173], v[172:173], 1, s[22:23]
	global_store_dwordx4 v[172:173], v[168:171], off
.LBB0_1263:
	global_load_dwordx4 v[168:171], v[196:197], off offset:512 nt
	s_nop 0
	global_load_dwordx4 v[180:183], v[196:197], off offset:528 nt
	s_and_b64 vcc, exec, s[8:9]
	s_waitcnt vmcnt(1)
	v_pk_fma_f32 v[38:39], v[38:39], v[136:137], v[170:171]
	v_pk_fma_f32 v[36:37], v[36:37], v[134:135], v[168:169]
	s_waitcnt vmcnt(0)
	v_pk_fma_f32 v[34:35], v[34:35], v[132:133], v[182:183]
	v_pk_fma_f32 v[32:33], v[32:33], v[130:131], v[180:181]
	global_store_dwordx4 v[194:195], v[36:39], off offset:512
	global_store_dwordx4 v[194:195], v[32:35], off offset:528
	s_cbranch_vccnz .LBB0_1265
	v_lshl_add_u64 v[172:173], v[174:175], 0, v[184:185]
	v_pk_mul_f32 v[170:171], v[228:229], v[38:39]
	v_pk_mul_f32 v[168:169], v[226:227], v[36:37]
	v_pk_mul_f32 v[174:175], v[224:225], v[34:35]
	v_pk_mul_f32 v[180:181], v[220:221], v[32:33]
	v_cvt_pk_bf16_f32 v168, v168, v169
	v_cvt_pk_bf16_f32 v169, v170, v171
	v_cvt_pk_bf16_f32 v170, v180, v181
	v_cvt_pk_bf16_f32 v171, v174, v175
	v_lshl_add_u64 v[172:173], v[172:173], 1, s[22:23]
	global_store_dwordx4 v[172:173], v[168:171], off
; __device__ __forceinline__ unsigned cvt_pk_bf16(float lo, float hi) { const f32x2 v = {lo, hi}; return __builtin_bit_cast(unsigned, __builtin_convertvector(v, bf16x2_t)); }
; __device__ __forceinline__ float dot4(f32x4 v) { return (v.x * v.x + v.y * v.y) + (v.z * v.z + v.w * v.w); }
;     template <int A0, int A1> __device__ __forceinline__ void run(const f32x4 (&acc)[2][2][4][2], const Unit& u, int wr, int wc, int fr, int fq) const {
;     ...
;             for (int ai = A0; ai < A1; ++ai)
; #pragma unroll
;                 for (int m = 0; m < 4; ++m) {
;                     const size_t off = (size_t)(row0 + ai * 128 + m * 16) * DM + col;
;                     const f32x4 x0 = *(const f32x4*)(xo + off) + gv0 * acc[ai][bj][m][0];
;                     const f32x4 x1 = *(const f32x4*)(xo + off + 4) + gv1 * acc[ai][bj][m][1];
;                     *(f32x4*)(xn + off) = x0; *(f32x4*)(xn + off + 4) = x1;
;                     ssq[ai][m] += dot4(x0) + dot4(x1);
;                     if (has_next) { const f32x4 y0 = x0 * wv0, y1 = x1 * wv1; u32x4 w; w.x = cvt_pk_bf16(y0.x, y0.y); w.y = cvt_pk_bf16(y0.z, y0.w); w.z = cvt_pk_bf16(y1.x, y1.y); w.w = cvt_pk_bf16(y1.z, y1.w); *(u32x4*)(Xw + off) = w; }
;                 }
.LBB0_1265:
	global_load_dwordx4 v[168:171], v[200:201], off offset:512 nt
	s_nop 0
	global_load_dwordx4 v[172:175], v[200:201], off offset:528 nt
	s_and_b64 vcc, exec, s[8:9]
	s_waitcnt vmcnt(1)
	v_pk_fma_f32 v[30:31], v[30:31], v[136:137], v[170:171]
	v_pk_fma_f32 v[28:29], v[28:29], v[134:135], v[168:169]
	s_waitcnt vmcnt(0)
	v_pk_fma_f32 v[26:27], v[26:27], v[132:133], v[174:175]
	v_pk_fma_f32 v[24:25], v[24:25], v[130:131], v[172:173]
	global_store_dwordx4 v[198:199], v[28:31], off offset:512
	global_store_dwordx4 v[198:199], v[24:27], off offset:528
	s_cbranch_vccnz .LBB0_1267
	v_lshl_add_u64 v[172:173], v[176:177], 0, v[184:185]
	v_pk_mul_f32 v[170:171], v[228:229], v[30:31]
	v_pk_mul_f32 v[168:169], v[226:227], v[28:29]
	v_pk_mul_f32 v[174:175], v[224:225], v[26:27]
	v_pk_mul_f32 v[176:177], v[220:221], v[24:25]
	v_cvt_pk_bf16_f32 v168, v168, v169
	v_cvt_pk_bf16_f32 v169, v170, v171
	v_cvt_pk_bf16_f32 v170, v176, v177
	v_cvt_pk_bf16_f32 v171, v174, v175
	v_lshl_add_u64 v[172:173], v[172:173], 1, s[22:23]
	global_store_dwordx4 v[172:173], v[168:171], off
.LBB0_1267:
	global_load_dwordx4 v[168:171], v[204:205], off offset:512 nt
	s_nop 0
	global_load_dwordx4 v[172:175], v[204:205], off offset:528 nt
	s_and_b64 vcc, exec, s[8:9]
	s_waitcnt vmcnt(1)
	v_pk_fma_f32 v[22:23], v[22:23], v[136:137], v[170:171]
	v_pk_fma_f32 v[20:21], v[20:21], v[134:135], v[168:169]
	s_waitcnt vmcnt(0)
	v_pk_fma_f32 v[18:19], v[18:19], v[132:133], v[174:175]
	v_pk_fma_f32 v[16:17], v[16:17], v[130:131], v[172:173]
	global_store_dwordx4 v[202:203], v[20:23], off offset:512
	global_store_dwordx4 v[202:203], v[16:19], off offset:528
	s_cbranch_vccnz .LBB0_1269
	v_lshl_add_u64 v[172:173], v[178:179], 0, v[184:185]
	v_pk_mul_f32 v[170:171], v[228:229], v[22:23]
	v_pk_mul_f32 v[168:169], v[226:227], v[20:21]
	v_pk_mul_f32 v[174:175], v[224:225], v[18:19]
	v_pk_mul_f32 v[176:177], v[220:221], v[16:17]
	v_cvt_pk_bf16_f32 v168, v168, v169
	v_cvt_pk_bf16_f32 v169, v170, v171
	v_cvt_pk_bf16_f32 v170, v176, v177
	v_cvt_pk_bf16_f32 v171, v174, v175
	v_lshl_add_u64 v[172:173], v[172:173], 1, s[22:23]
	global_store_dwordx4 v[172:173], v[168:171], off
.LBB0_1269:
	global_load_dwordx4 v[168:171], v[208:209], off offset:512 nt
	s_nop 0
	global_load_dwordx4 v[172:175], v[208:209], off offset:528 nt
	s_and_b64 vcc, exec, s[8:9]
	s_waitcnt vmcnt(1)
	v_pk_fma_f32 v[14:15], v[14:15], v[136:137], v[170:171]
	v_pk_fma_f32 v[12:13], v[12:13], v[134:135], v[168:169]
	s_waitcnt vmcnt(0)
	v_pk_fma_f32 v[10:11], v[10:11], v[132:133], v[174:175]
	v_pk_fma_f32 v[8:9], v[8:9], v[130:131], v[172:173]
	global_store_dwordx4 v[206:207], v[12:15], off offset:512
	global_store_dwordx4 v[206:207], v[8:11], off offset:528
	s_cbranch_vccnz .LBB0_1271
	v_lshl_add_u64 v[172:173], v[190:191], 0, v[184:185]
	v_pk_mul_f32 v[170:171], v[228:229], v[14:15]
	v_pk_mul_f32 v[168:169], v[226:227], v[12:13]
	v_pk_mul_f32 v[174:175], v[224:225], v[10:11]
	v_pk_mul_f32 v[176:177], v[220:221], v[8:9]
	v_cvt_pk_bf16_f32 v168, v168, v169
	v_cvt_pk_bf16_f32 v169, v170, v171
	v_cvt_pk_bf16_f32 v170, v176, v177
	v_cvt_pk_bf16_f32 v171, v174, v175
	v_lshl_add_u64 v[172:173], v[172:173], 1, s[22:23]
	global_store_dwordx4 v[172:173], v[168:171], off
.LBB0_1271:
	global_load_dwordx4 v[168:171], v[212:213], off offset:512 nt
	s_nop 0
	global_load_dwordx4 v[172:175], v[212:213], off offset:528 nt
	s_and_b64 vcc, exec, s[8:9]
	s_waitcnt vmcnt(1)
	v_pk_fma_f32 v[6:7], v[6:7], v[136:137], v[170:171]
	v_pk_fma_f32 v[4:5], v[4:5], v[134:135], v[168:169]
	s_waitcnt vmcnt(0)
	v_pk_fma_f32 v[2:3], v[2:3], v[132:133], v[174:175]
	v_pk_fma_f32 v[0:1], v[0:1], v[130:131], v[172:173]
	global_store_dwordx4 v[210:211], v[4:7], off offset:512
	global_store_dwordx4 v[210:211], v[0:3], off offset:528
	s_cbranch_vccnz .LBB0_1273
	v_lshl_add_u64 v[134:135], v[192:193], 0, v[184:185]
	v_pk_mul_f32 v[132:133], v[228:229], v[6:7]
	v_pk_mul_f32 v[130:131], v[226:227], v[4:5]
	v_pk_mul_f32 v[136:137], v[224:225], v[2:3]
	v_pk_mul_f32 v[168:169], v[220:221], v[0:1]
	v_cvt_pk_bf16_f32 v130, v130, v131
	v_cvt_pk_bf16_f32 v131, v132, v133
	v_cvt_pk_bf16_f32 v132, v168, v169
	v_cvt_pk_bf16_f32 v133, v136, v137
	v_lshl_add_u64 v[134:135], v[134:135], 1, s[22:23]
	global_store_dwordx4 v[134:135], v[130:133], off
